# attention unit epilogue: all 8 gate loads issued together at the top into the dead K/V prefetch registers, one wait, no store drains (was a ladder of load/store round trips)
# baseline (speedup 1.0000x reference)
.LBB0_827:
	s_or_b64 exec, exec, s[34:35]
	s_movk_i32 s0, 0xef
	v_or_b32_e32 v20, v138, v158
	v_ashrrev_i32_e32 v21, 31, v20
	v_lshlrev_b64 v[20:21], 1, v[20:21]
	v_cmp_lt_i32_e64 s[6:7], s0, v164
	s_nop 3
	s_and_saveexec_b64 s[8:9], s[6:7]
	v_add_u32_e32 v172, 0xffffff10, v164
	v_lshl_add_u64 v[22:23], v[134:135], 0, v[172:173]
	v_lshlrev_b64 v[22:23], 12, v[22:23]
	v_lshl_add_u64 v[22:23], s[54:55], 0, v[22:23]
	v_lshl_add_u64 v[22:23], v[22:23], 0, v[20:21]
	global_load_dwordx2 v[36:37], v[22:23], off offset:2048
	global_load_dwordx2 v[38:39], v[22:23], off offset:2080
	global_load_dwordx2 v[40:41], v[22:23], off offset:2112
	global_load_dwordx2 v[42:43], v[22:23], off offset:2144
	s_mov_b64 exec, s[8:9]
	v_cmp_lt_i32_e64 s[6:7], s0, v139
	s_nop 3
	s_and_saveexec_b64 s[8:9], s[6:7]
	v_add_u32_e32 v172, 0xffffff20, v164
	v_lshl_add_u64 v[24:25], v[134:135], 0, v[172:173]
	v_lshlrev_b64 v[24:25], 12, v[24:25]
	v_lshl_add_u64 v[24:25], s[54:55], 0, v[24:25]
	v_lshl_add_u64 v[24:25], v[24:25], 0, v[20:21]
	global_load_dwordx2 v[44:45], v[24:25], off offset:2048
	global_load_dwordx2 v[46:47], v[24:25], off offset:2080
	global_load_dwordx2 v[48:49], v[24:25], off offset:2112
	global_load_dwordx2 v[50:51], v[24:25], off offset:2144
	s_mov_b64 exec, s[8:9]
	ds_bpermute_b32 v20, v160, v136
	s_movk_i32 s0, 0xef
	v_cmp_lt_i32_e64 s[6:7], s0, v164
	s_waitcnt lgkmcnt(0)
	v_add_f32_e32 v22, v136, v20
	ds_bpermute_b32 v23, v161, v22
	v_or_b32_e32 v20, v138, v158
	v_ashrrev_i32_e32 v21, 31, v20
	s_and_saveexec_b64 s[8:9], s[6:7]
	s_cbranch_execz .Lattn_epi_skip1
	v_add_u32_e32 v172, 0xffffff10, v164
	v_lshl_add_u64 v[24:25], v[134:135], 0, v[172:173]
	v_lshlrev_b64 v[26:27], 12, v[24:25]
	v_lshl_add_u64 v[26:27], s[54:55], 0, v[26:27]
	v_lshlrev_b64 v[28:29], 1, v[20:21]
	v_lshl_add_u64 v[26:27], v[26:27], 0, v[28:29]
	v_lshlrev_b64 v[24:25], 11, v[24:25]
	v_lshl_add_u64 v[24:25], s[44:45], 0, v[24:25]
	v_lshl_add_u64 v[24:25], v[24:25], 0, v[28:29]
	s_waitcnt lgkmcnt(0)
	v_add_f32_e32 v22, v22, v23
	v_rcp_f32_e32 v22, v22
	v_mov_b32_e32 v34, v68
	v_mov_b32_e32 v35, v70
	v_mov_b32_e32 v70, v69
	s_waitcnt vmcnt(0)
	v_mov_b32_e32 v30, v36
	v_mov_b32_e32 v31, v37
	v_lshlrev_b32_e32 v23, 16, v30
	v_mul_f32_e32 v23, 0xbfb8aa3b, v23
	v_exp_f32_e32 v23, v23
	s_nop 0
	v_add_f32_e32 v23, 1.0, v23
	v_rcp_f32_e32 v32, v23
	v_and_b32_e32 v23, 0xffff0000, v30
	v_mul_f32_e32 v23, 0xbfb8aa3b, v23
	v_exp_f32_e32 v23, v23
	s_nop 0
	v_add_f32_e32 v23, 1.0, v23
	v_rcp_f32_e32 v30, v23
	v_lshlrev_b32_e32 v23, 16, v31
	v_mul_f32_e32 v23, 0xbfb8aa3b, v23
	v_exp_f32_e32 v23, v23
	s_nop 0
	v_add_f32_e32 v23, 1.0, v23
	v_rcp_f32_e32 v33, v23
	v_and_b32_e32 v23, 0xffff0000, v31
	v_mul_f32_e32 v23, 0xbfb8aa3b, v23
	v_exp_f32_e32 v23, v23
	s_nop 0
	v_add_f32_e32 v23, 1.0, v23
	v_rcp_f32_e32 v31, v23
	v_pk_mul_f32 v[34:35], v[34:35], v[22:23] op_sel_hi:[1,0]
	s_nop 0
	v_pk_mul_f32 v[32:33], v[34:35], v[32:33]
	v_pk_mul_f32 v[34:35], v[70:71], v[22:23] op_sel_hi:[1,0]
	v_and_b32_sdwa v23, v33, v196 dst_sel:DWORD dst_unused:UNUSED_PAD src0_sel:WORD_1 src1_sel:DWORD
	v_pk_mul_f32 v[30:31], v[34:35], v[30:31]
	v_add3_u32 v23, v33, v23, s96
	v_and_b32_sdwa v33, v31, v196 dst_sel:DWORD dst_unused:UNUSED_PAD src0_sel:WORD_1 src1_sel:DWORD
	v_add3_u32 v31, v31, v33, s96
	v_and_b32_e32 v31, 0xffff0000, v31
	v_or_b32_sdwa v31, v31, v23 dst_sel:DWORD dst_unused:UNUSED_PAD src0_sel:DWORD src1_sel:WORD_1
	v_mov_b32_e32 v28, v38
	v_mov_b32_e32 v29, v39
	v_lshlrev_b32_e32 v23, 16, v28
	v_mul_f32_e32 v23, 0xbfb8aa3b, v23
	v_and_b32_sdwa v34, v32, v196 dst_sel:DWORD dst_unused:UNUSED_PAD src0_sel:WORD_1 src1_sel:DWORD
	v_exp_f32_e32 v23, v23
	v_add3_u32 v32, v32, v34, s96
	v_and_b32_sdwa v34, v30, v196 dst_sel:DWORD dst_unused:UNUSED_PAD src0_sel:WORD_1 src1_sel:DWORD
	v_add3_u32 v30, v30, v34, s96
	v_and_b32_e32 v30, 0xffff0000, v30
	v_or_b32_sdwa v30, v30, v32 dst_sel:DWORD dst_unused:UNUSED_PAD src0_sel:DWORD src1_sel:WORD_1
	v_add_f32_e32 v23, 1.0, v23
	global_store_dwordx2 v[24:25], v[30:31], off
	v_rcp_f32_e32 v30, v23
	v_and_b32_e32 v23, 0xffff0000, v28
	v_mul_f32_e32 v23, 0xbfb8aa3b, v23
	v_exp_f32_e32 v23, v23
	v_mov_b32_e32 v32, v64
	v_mov_b32_e32 v33, v66
	v_mov_b32_e32 v66, v65
	v_add_f32_e32 v23, 1.0, v23
	v_rcp_f32_e32 v28, v23
	v_lshlrev_b32_e32 v23, 16, v29
	v_mul_f32_e32 v23, 0xbfb8aa3b, v23
	v_exp_f32_e32 v23, v23
	s_nop 0
	v_add_f32_e32 v23, 1.0, v23
	v_rcp_f32_e32 v31, v23
	v_and_b32_e32 v23, 0xffff0000, v29
	v_mul_f32_e32 v23, 0xbfb8aa3b, v23
	v_exp_f32_e32 v23, v23
	s_nop 0
	v_add_f32_e32 v23, 1.0, v23
	v_rcp_f32_e32 v29, v23
	v_pk_mul_f32 v[32:33], v[32:33], v[22:23] op_sel_hi:[1,0]
	s_nop 0
	v_pk_mul_f32 v[30:31], v[32:33], v[30:31]
	v_pk_mul_f32 v[32:33], v[66:67], v[22:23] op_sel_hi:[1,0]
	v_and_b32_sdwa v23, v31, v196 dst_sel:DWORD dst_unused:UNUSED_PAD src0_sel:WORD_1 src1_sel:DWORD
	v_pk_mul_f32 v[28:29], v[32:33], v[28:29]
	v_and_b32_sdwa v32, v30, v196 dst_sel:DWORD dst_unused:UNUSED_PAD src0_sel:WORD_1 src1_sel:DWORD
	v_add3_u32 v30, v30, v32, s96
	v_add3_u32 v23, v31, v23, s96
	v_and_b32_sdwa v31, v29, v196 dst_sel:DWORD dst_unused:UNUSED_PAD src0_sel:WORD_1 src1_sel:DWORD
	v_and_b32_sdwa v32, v28, v196 dst_sel:DWORD dst_unused:UNUSED_PAD src0_sel:WORD_1 src1_sel:DWORD
	v_add3_u32 v29, v29, v31, s96
	v_add3_u32 v28, v28, v32, s96
	v_and_b32_e32 v29, 0xffff0000, v29
	v_and_b32_e32 v28, 0xffff0000, v28
	v_or_b32_sdwa v29, v29, v23 dst_sel:DWORD dst_unused:UNUSED_PAD src0_sel:DWORD src1_sel:WORD_1
	v_or_b32_sdwa v28, v28, v30 dst_sel:DWORD dst_unused:UNUSED_PAD src0_sel:DWORD src1_sel:WORD_1
	global_store_dwordx2 v[24:25], v[28:29], off offset:32
	v_mov_b32_e32 v32, v60
	v_mov_b32_e32 v33, v62
	v_mov_b32_e32 v62, v61
	v_mov_b32_e32 v28, v40
	v_mov_b32_e32 v29, v41
	v_lshlrev_b32_e32 v23, 16, v28
	v_mul_f32_e32 v23, 0xbfb8aa3b, v23
	v_exp_f32_e32 v23, v23
	s_nop 0
	v_add_f32_e32 v23, 1.0, v23
	v_rcp_f32_e32 v30, v23
	v_and_b32_e32 v23, 0xffff0000, v28
	v_mul_f32_e32 v23, 0xbfb8aa3b, v23
	v_exp_f32_e32 v23, v23
	s_nop 0
	v_add_f32_e32 v23, 1.0, v23
	v_rcp_f32_e32 v28, v23
	v_lshlrev_b32_e32 v23, 16, v29
	v_mul_f32_e32 v23, 0xbfb8aa3b, v23
	v_exp_f32_e32 v23, v23
	s_nop 0
	v_add_f32_e32 v23, 1.0, v23
	v_rcp_f32_e32 v31, v23
	v_and_b32_e32 v23, 0xffff0000, v29
	v_mul_f32_e32 v23, 0xbfb8aa3b, v23
	v_exp_f32_e32 v23, v23
	s_nop 0
	v_add_f32_e32 v23, 1.0, v23
	v_rcp_f32_e32 v29, v23
	v_pk_mul_f32 v[32:33], v[32:33], v[22:23] op_sel_hi:[1,0]
	s_nop 0
	v_pk_mul_f32 v[30:31], v[32:33], v[30:31]
	v_pk_mul_f32 v[32:33], v[62:63], v[22:23] op_sel_hi:[1,0]
	v_and_b32_sdwa v23, v31, v196 dst_sel:DWORD dst_unused:UNUSED_PAD src0_sel:WORD_1 src1_sel:DWORD
	v_pk_mul_f32 v[28:29], v[32:33], v[28:29]
	v_add3_u32 v23, v31, v23, s96
	v_and_b32_sdwa v31, v29, v196 dst_sel:DWORD dst_unused:UNUSED_PAD src0_sel:WORD_1 src1_sel:DWORD
	v_add3_u32 v29, v29, v31, s96
	v_and_b32_e32 v29, 0xffff0000, v29
	v_or_b32_sdwa v29, v29, v23 dst_sel:DWORD dst_unused:UNUSED_PAD src0_sel:DWORD src1_sel:WORD_1
	v_mov_b32_e32 v26, v42
	v_mov_b32_e32 v27, v43
	v_lshlrev_b32_e32 v23, 16, v26
	v_mul_f32_e32 v23, 0xbfb8aa3b, v23
	v_and_b32_sdwa v32, v30, v196 dst_sel:DWORD dst_unused:UNUSED_PAD src0_sel:WORD_1 src1_sel:DWORD
	v_exp_f32_e32 v23, v23
	v_add3_u32 v30, v30, v32, s96
	v_and_b32_sdwa v32, v28, v196 dst_sel:DWORD dst_unused:UNUSED_PAD src0_sel:WORD_1 src1_sel:DWORD
	v_add3_u32 v28, v28, v32, s96
	v_and_b32_e32 v28, 0xffff0000, v28
	v_or_b32_sdwa v28, v28, v30 dst_sel:DWORD dst_unused:UNUSED_PAD src0_sel:DWORD src1_sel:WORD_1
	v_add_f32_e32 v23, 1.0, v23
	global_store_dwordx2 v[24:25], v[28:29], off offset:64
	v_rcp_f32_e32 v28, v23
	v_and_b32_e32 v23, 0xffff0000, v26
	v_mul_f32_e32 v23, 0xbfb8aa3b, v23
	v_exp_f32_e32 v23, v23
	v_mov_b32_e32 v31, v18
	v_mov_b32_e32 v18, v17
	v_mov_b32_e32 v30, v16
	v_add_f32_e32 v23, 1.0, v23
	v_rcp_f32_e32 v26, v23
	v_lshlrev_b32_e32 v23, 16, v27
	v_mul_f32_e32 v23, 0xbfb8aa3b, v23
	v_exp_f32_e32 v23, v23
	s_nop 0
	v_add_f32_e32 v23, 1.0, v23
	v_rcp_f32_e32 v29, v23
	v_and_b32_e32 v23, 0xffff0000, v27
	v_mul_f32_e32 v23, 0xbfb8aa3b, v23
	v_exp_f32_e32 v23, v23
	s_nop 0
	v_add_f32_e32 v23, 1.0, v23
	v_rcp_f32_e32 v27, v23
	v_pk_mul_f32 v[16:17], v[18:19], v[22:23] op_sel_hi:[1,0]
	v_pk_mul_f32 v[30:31], v[30:31], v[22:23] op_sel_hi:[1,0]
	v_pk_mul_f32 v[16:17], v[16:17], v[26:27]
	v_pk_mul_f32 v[28:29], v[30:31], v[28:29]
	v_and_b32_sdwa v22, v17, v196 dst_sel:DWORD dst_unused:UNUSED_PAD src0_sel:WORD_1 src1_sel:DWORD
	v_and_b32_sdwa v23, v16, v196 dst_sel:DWORD dst_unused:UNUSED_PAD src0_sel:WORD_1 src1_sel:DWORD
	v_and_b32_sdwa v18, v29, v196 dst_sel:DWORD dst_unused:UNUSED_PAD src0_sel:WORD_1 src1_sel:DWORD
	v_and_b32_sdwa v19, v28, v196 dst_sel:DWORD dst_unused:UNUSED_PAD src0_sel:WORD_1 src1_sel:DWORD
	v_add3_u32 v17, v17, v22, s96
	v_add3_u32 v16, v16, v23, s96
	v_add3_u32 v19, v28, v19, s96
	v_add3_u32 v18, v29, v18, s96
	v_and_b32_e32 v17, 0xffff0000, v17
	v_and_b32_e32 v16, 0xffff0000, v16
	v_or_b32_sdwa v17, v17, v18 dst_sel:DWORD dst_unused:UNUSED_PAD src0_sel:DWORD src1_sel:WORD_1
	v_or_b32_sdwa v16, v16, v19 dst_sel:DWORD dst_unused:UNUSED_PAD src0_sel:DWORD src1_sel:WORD_1
	global_store_dwordx2 v[24:25], v[16:17], off offset:96
.LBB0_829:
	s_or_b64 exec, exec, s[8:9]
	ds_bpermute_b32 v16, v160, v137
	v_cmp_lt_i32_e64 s[6:7], s0, v139
	s_waitcnt lgkmcnt(0)
	v_add_f32_e32 v16, v137, v16
	ds_bpermute_b32 v17, v161, v16
	s_and_saveexec_b64 s[8:9], s[6:7]
	s_xor_b64 s[6:7], exec, s[8:9]
	s_movk_i32 s73, 0x4000
	s_mov_b32 s76, 0x3f317217
	s_mov_b32 s77, 0x7f800000
	s_movk_i32 s84, 0x407f
	s_mov_b32 s87, s60
	s_cbranch_execz .LBB0_788
	v_add_u32_e32 v172, 0xffffff20, v164
	v_lshl_add_u64 v[18:19], v[134:135], 0, v[172:173]
	v_lshlrev_b64 v[22:23], 12, v[18:19]
	v_lshl_add_u64 v[22:23], s[54:55], 0, v[22:23]
	v_lshlrev_b64 v[18:19], 11, v[18:19]
	v_lshlrev_b64 v[20:21], 1, v[20:21]
	v_lshl_add_u64 v[24:25], s[44:45], 0, v[18:19]
	v_lshl_add_u64 v[18:19], v[22:23], 0, v[20:21]
	s_waitcnt lgkmcnt(0)
	v_add_f32_e32 v16, v16, v17
	v_rcp_f32_e32 v16, v16
	v_mov_b32_e32 v28, v12
	v_mov_b32_e32 v29, v14
	v_mov_b32_e32 v14, v13
	s_waitcnt vmcnt(4)
	v_mov_b32_e32 v22, v44
	v_mov_b32_e32 v23, v45
	v_lshlrev_b32_e32 v17, 16, v22
	v_mul_f32_e32 v17, 0xbfb8aa3b, v17
	v_exp_f32_e32 v17, v17
	s_nop 0
	v_add_f32_e32 v17, 1.0, v17
	v_rcp_f32_e32 v26, v17
	v_and_b32_e32 v17, 0xffff0000, v22
	v_mul_f32_e32 v17, 0xbfb8aa3b, v17
	v_exp_f32_e32 v17, v17
	s_nop 0
	v_add_f32_e32 v17, 1.0, v17
	v_rcp_f32_e32 v22, v17
	v_lshlrev_b32_e32 v17, 16, v23
	v_mul_f32_e32 v17, 0xbfb8aa3b, v17
	v_exp_f32_e32 v17, v17
	s_nop 0
	v_add_f32_e32 v17, 1.0, v17
	v_rcp_f32_e32 v27, v17
	v_and_b32_e32 v17, 0xffff0000, v23
	v_mul_f32_e32 v17, 0xbfb8aa3b, v17
	v_exp_f32_e32 v17, v17
	s_nop 0
	v_add_f32_e32 v17, 1.0, v17
	v_rcp_f32_e32 v23, v17
	v_pk_mul_f32 v[28:29], v[28:29], v[16:17] op_sel_hi:[1,0]
	v_pk_mul_f32 v[12:13], v[14:15], v[16:17] op_sel_hi:[1,0]
	v_pk_mul_f32 v[26:27], v[28:29], v[26:27]
	v_pk_mul_f32 v[12:13], v[12:13], v[22:23]
	v_and_b32_sdwa v15, v26, v196 dst_sel:DWORD dst_unused:UNUSED_PAD src0_sel:WORD_1 src1_sel:DWORD
	v_add3_u32 v17, v26, v15, s96
	v_and_b32_sdwa v15, v13, v196 dst_sel:DWORD dst_unused:UNUSED_PAD src0_sel:WORD_1 src1_sel:DWORD
	v_and_b32_sdwa v22, v12, v196 dst_sel:DWORD dst_unused:UNUSED_PAD src0_sel:WORD_1 src1_sel:DWORD
	v_and_b32_sdwa v14, v27, v196 dst_sel:DWORD dst_unused:UNUSED_PAD src0_sel:WORD_1 src1_sel:DWORD
	v_add3_u32 v13, v13, v15, s96
	v_add3_u32 v12, v12, v22, s96
	v_add3_u32 v14, v27, v14, s96
	v_and_b32_e32 v13, 0xffff0000, v13
	v_and_b32_e32 v12, 0xffff0000, v12
	v_or_b32_sdwa v15, v13, v14 dst_sel:DWORD dst_unused:UNUSED_PAD src0_sel:DWORD src1_sel:WORD_1
	v_or_b32_sdwa v14, v12, v17 dst_sel:DWORD dst_unused:UNUSED_PAD src0_sel:DWORD src1_sel:WORD_1
	v_lshl_add_u64 v[12:13], v[24:25], 0, v[20:21]
	global_store_dwordx2 v[12:13], v[14:15], off
	v_mov_b32_e32 v23, v10
	v_mov_b32_e32 v10, v9
	v_mov_b32_e32 v22, v8
	v_mov_b32_e32 v14, v46
	v_mov_b32_e32 v15, v47
	v_lshlrev_b32_e32 v17, 16, v14
	v_mul_f32_e32 v17, 0xbfb8aa3b, v17
	v_exp_f32_e32 v17, v17
	v_and_b32_e32 v14, 0xffff0000, v14
	v_mul_f32_e32 v14, 0xbfb8aa3b, v14
	v_exp_f32_e32 v14, v14
	v_add_f32_e32 v17, 1.0, v17
	v_rcp_f32_e32 v20, v17
	v_lshlrev_b32_e32 v17, 16, v15
	v_and_b32_e32 v15, 0xffff0000, v15
	v_mul_f32_e32 v15, 0xbfb8aa3b, v15
	v_mul_f32_e32 v17, 0xbfb8aa3b, v17
	v_exp_f32_e32 v15, v15
	v_exp_f32_e32 v17, v17
	v_add_f32_e32 v14, 1.0, v14
	v_rcp_f32_e32 v14, v14
	v_add_f32_e32 v15, 1.0, v15
	v_add_f32_e32 v17, 1.0, v17
	v_rcp_f32_e32 v15, v15
	v_rcp_f32_e32 v21, v17
	v_pk_mul_f32 v[8:9], v[10:11], v[16:17] op_sel_hi:[1,0]
	v_pk_mul_f32 v[22:23], v[22:23], v[16:17] op_sel_hi:[1,0]
	v_pk_mul_f32 v[8:9], v[8:9], v[14:15]
	v_pk_mul_f32 v[20:21], v[22:23], v[20:21]
	v_and_b32_sdwa v14, v9, v196 dst_sel:DWORD dst_unused:UNUSED_PAD src0_sel:WORD_1 src1_sel:DWORD
	v_and_b32_sdwa v15, v8, v196 dst_sel:DWORD dst_unused:UNUSED_PAD src0_sel:WORD_1 src1_sel:DWORD
	v_and_b32_sdwa v10, v21, v196 dst_sel:DWORD dst_unused:UNUSED_PAD src0_sel:WORD_1 src1_sel:DWORD
	v_and_b32_sdwa v11, v20, v196 dst_sel:DWORD dst_unused:UNUSED_PAD src0_sel:WORD_1 src1_sel:DWORD
	v_add3_u32 v9, v9, v14, s96
	v_add3_u32 v8, v8, v15, s96
	v_add3_u32 v11, v20, v11, s96
	v_add3_u32 v10, v21, v10, s96
	v_and_b32_e32 v9, 0xffff0000, v9
	v_and_b32_e32 v8, 0xffff0000, v8
	v_or_b32_sdwa v9, v9, v10 dst_sel:DWORD dst_unused:UNUSED_PAD src0_sel:DWORD src1_sel:WORD_1
	v_or_b32_sdwa v8, v8, v11 dst_sel:DWORD dst_unused:UNUSED_PAD src0_sel:DWORD src1_sel:WORD_1
	global_store_dwordx2 v[12:13], v[8:9], off offset:32
	v_mov_b32_e32 v15, v6
	v_mov_b32_e32 v6, v5
	v_mov_b32_e32 v14, v4
	v_pk_mul_f32 v[4:5], v[6:7], v[16:17] op_sel_hi:[1,0]
	v_pk_mul_f32 v[14:15], v[14:15], v[16:17] op_sel_hi:[1,0]
	v_mov_b32_e32 v8, v48
	v_mov_b32_e32 v9, v49
	v_lshlrev_b32_e32 v10, 16, v8
	v_and_b32_e32 v8, 0xffff0000, v8
	v_lshlrev_b32_e32 v11, 16, v9
	v_and_b32_e32 v9, 0xffff0000, v9
	v_mul_f32_e32 v8, 0xbfb8aa3b, v8
	v_mul_f32_e32 v9, 0xbfb8aa3b, v9
	v_mul_f32_e32 v10, 0xbfb8aa3b, v10
	v_exp_f32_e32 v8, v8
	v_mul_f32_e32 v11, 0xbfb8aa3b, v11
	v_exp_f32_e32 v9, v9
	v_exp_f32_e32 v10, v10
	v_exp_f32_e32 v11, v11
	v_add_f32_e32 v8, 1.0, v8
	v_add_f32_e32 v9, 1.0, v9
	v_add_f32_e32 v10, 1.0, v10
	v_rcp_f32_e32 v8, v8
	v_add_f32_e32 v11, 1.0, v11
	v_rcp_f32_e32 v9, v9
	v_rcp_f32_e32 v10, v10
	v_rcp_f32_e32 v11, v11
	v_pk_mul_f32 v[4:5], v[4:5], v[8:9]
	s_nop 0
	v_and_b32_sdwa v8, v5, v196 dst_sel:DWORD dst_unused:UNUSED_PAD src0_sel:WORD_1 src1_sel:DWORD
	v_pk_mul_f32 v[10:11], v[14:15], v[10:11]
	v_and_b32_sdwa v9, v4, v196 dst_sel:DWORD dst_unused:UNUSED_PAD src0_sel:WORD_1 src1_sel:DWORD
	v_and_b32_sdwa v6, v11, v196 dst_sel:DWORD dst_unused:UNUSED_PAD src0_sel:WORD_1 src1_sel:DWORD
	v_and_b32_sdwa v7, v10, v196 dst_sel:DWORD dst_unused:UNUSED_PAD src0_sel:WORD_1 src1_sel:DWORD
	v_add3_u32 v5, v5, v8, s96
	v_add3_u32 v4, v4, v9, s96
	v_add3_u32 v7, v10, v7, s96
	v_add3_u32 v6, v11, v6, s96
	v_and_b32_e32 v5, 0xffff0000, v5
	v_and_b32_e32 v4, 0xffff0000, v4
	v_or_b32_sdwa v5, v5, v6 dst_sel:DWORD dst_unused:UNUSED_PAD src0_sel:DWORD src1_sel:WORD_1
	v_or_b32_sdwa v4, v4, v7 dst_sel:DWORD dst_unused:UNUSED_PAD src0_sel:DWORD src1_sel:WORD_1
	global_store_dwordx2 v[12:13], v[4:5], off offset:64
	v_mov_b32_e32 v9, v2
	v_mov_b32_e32 v2, v1
	v_mov_b32_e32 v8, v0
	v_pk_mul_f32 v[0:1], v[2:3], v[16:17] op_sel_hi:[1,0]
	v_pk_mul_f32 v[8:9], v[8:9], v[16:17] op_sel_hi:[1,0]
	v_mov_b32_e32 v4, v50
	v_mov_b32_e32 v5, v51
	v_lshlrev_b32_e32 v6, 16, v4
	v_and_b32_e32 v4, 0xffff0000, v4
	v_lshlrev_b32_e32 v7, 16, v5
	v_and_b32_e32 v5, 0xffff0000, v5
	v_mul_f32_e32 v4, 0xbfb8aa3b, v4
	v_mul_f32_e32 v5, 0xbfb8aa3b, v5
	v_mul_f32_e32 v6, 0xbfb8aa3b, v6
	v_exp_f32_e32 v4, v4
	v_mul_f32_e32 v7, 0xbfb8aa3b, v7
	v_exp_f32_e32 v5, v5
	v_exp_f32_e32 v6, v6
	v_exp_f32_e32 v7, v7
	v_add_f32_e32 v4, 1.0, v4
	v_add_f32_e32 v5, 1.0, v5
	v_add_f32_e32 v6, 1.0, v6
	v_rcp_f32_e32 v4, v4
	v_add_f32_e32 v7, 1.0, v7
	v_rcp_f32_e32 v5, v5
	v_rcp_f32_e32 v6, v6
	v_rcp_f32_e32 v7, v7
	v_pk_mul_f32 v[0:1], v[0:1], v[4:5]
	s_nop 0
	v_and_b32_sdwa v4, v1, v196 dst_sel:DWORD dst_unused:UNUSED_PAD src0_sel:WORD_1 src1_sel:DWORD
	v_pk_mul_f32 v[6:7], v[8:9], v[6:7]
	v_and_b32_sdwa v5, v0, v196 dst_sel:DWORD dst_unused:UNUSED_PAD src0_sel:WORD_1 src1_sel:DWORD
	v_and_b32_sdwa v2, v7, v196 dst_sel:DWORD dst_unused:UNUSED_PAD src0_sel:WORD_1 src1_sel:DWORD
	v_and_b32_sdwa v3, v6, v196 dst_sel:DWORD dst_unused:UNUSED_PAD src0_sel:WORD_1 src1_sel:DWORD
	v_add3_u32 v1, v1, v4, s96
	v_add3_u32 v0, v0, v5, s96
	v_add3_u32 v3, v6, v3, s96
	v_add3_u32 v2, v7, v2, s96
	v_and_b32_e32 v1, 0xffff0000, v1
	v_and_b32_e32 v0, 0xffff0000, v0
	v_or_b32_sdwa v1, v1, v2 dst_sel:DWORD dst_unused:UNUSED_PAD src0_sel:DWORD src1_sel:WORD_1
	v_or_b32_sdwa v0, v0, v3 dst_sel:DWORD dst_unused:UNUSED_PAD src0_sel:DWORD src1_sel:WORD_1
	global_store_dwordx2 v[12:13], v[0:1], off offset:96
	s_branch .LBB0_788
.Lattn_epi_skip1:
	s_waitcnt vmcnt(0)
	s_branch .LBB0_829
